# stick-breaking task epilogue: the 16 output-gain vector loads issued together (into the dead Q/K/V fragment registers) instead of a load-wait ladder
# speedup vs baseline: 1.0097x; 1.0019x over previous
; __device__ __forceinline__ void sb_task(ATT_LAS unsigned char* wl  , int b, int h, int qb, const bf16_t* __restrict__ SQ, const bf16_t* __restrict__ SK, const bf16_t* __restrict__ VT, const float* __restrict__ gout, bf16_t* __restrict__ MIXED) {
;     ...
;     float ss = 0.f;
; #pragma unroll
;     for (int e = 0; e < 4; ++e)
; #pragma unroll
;         for (int i = 0; i < 16; ++i) ss += O[e][i] * O[e][i];
;     ss += __shfl_xor(ss, 32);
;     const float rstd = rsqrtf(ss * (1.0f / 128.0f) + EPS);
; #pragma unroll
;     for (int e = 0; e < 4; ++e)
; #pragma unroll
;         for (int g4 = 0; g4 < 4; ++g4) { const int e0 = 32 * e + 8 * g4 + 4 * hh; const f32x4 g = *(const f32x4*)(gout + e0);
.LBB0_562:
	s_nop 2
	v_mul_f32_e32 v78, v49, v49
	global_load_dwordx4 v[80:83], v[152:153], off
	global_load_dwordx4 v[84:87], v[152:153], off offset:32
	global_load_dwordx4 v[88:91], v[152:153], off offset:64
	global_load_dwordx4 v[92:95], v[152:153], off offset:96
	global_load_dwordx4 v[96:99], v[152:153], off offset:128
	global_load_dwordx4 v[100:103], v[152:153], off offset:160
	global_load_dwordx4 v[104:107], v[152:153], off offset:192
	global_load_dwordx4 v[108:111], v[152:153], off offset:224
	global_load_dwordx4 v[112:115], v[152:153], off offset:256
	global_load_dwordx4 v[116:119], v[152:153], off offset:288
	global_load_dwordx4 v[120:123], v[152:153], off offset:320
	global_load_dwordx4 v[124:127], v[152:153], off offset:352
	global_load_dwordx4 v[128:131], v[152:153], off offset:384
	global_load_dwordx4 v[132:135], v[152:153], off offset:416
	global_load_dwordx4 v[136:139], v[152:153], off offset:448
	global_load_dwordx4 v[140:143], v[152:153], off offset:480
	v_fmac_f32_e32 v78, v48, v48
	v_fmac_f32_e32 v78, v50, v50
	v_fmac_f32_e32 v78, v51, v51
	v_fmac_f32_e32 v78, v52, v52
	v_fmac_f32_e32 v78, v53, v53
	v_fmac_f32_e32 v78, v54, v54
	v_fmac_f32_e32 v78, v55, v55
	v_fmac_f32_e32 v78, v56, v56
	v_fmac_f32_e32 v78, v57, v57
	v_fmac_f32_e32 v78, v58, v58
	v_fmac_f32_e32 v78, v59, v59
	v_fmac_f32_e32 v78, v60, v60
	v_fmac_f32_e32 v78, v61, v61
	v_fmac_f32_e32 v78, v62, v62
	v_fmac_f32_e32 v78, v63, v63
	v_fmac_f32_e32 v78, v32, v32
	v_fmac_f32_e32 v78, v33, v33
	v_fmac_f32_e32 v78, v34, v34
	v_fmac_f32_e32 v78, v35, v35
	v_fmac_f32_e32 v78, v36, v36
	v_fmac_f32_e32 v78, v37, v37
	v_fmac_f32_e32 v78, v38, v38
	v_fmac_f32_e32 v78, v39, v39
	v_fmac_f32_e32 v78, v40, v40
	v_fmac_f32_e32 v78, v41, v41
	v_fmac_f32_e32 v78, v42, v42
	v_fmac_f32_e32 v78, v43, v43
	v_fmac_f32_e32 v78, v44, v44
	v_fmac_f32_e32 v78, v45, v45
	v_fmac_f32_e32 v78, v46, v46
	v_fmac_f32_e32 v78, v47, v47
	v_fmac_f32_e32 v78, v16, v16
	v_fmac_f32_e32 v78, v17, v17
	v_fmac_f32_e32 v78, v18, v18
	v_fmac_f32_e32 v78, v19, v19
	v_fmac_f32_e32 v78, v20, v20
	v_fmac_f32_e32 v78, v21, v21
	v_fmac_f32_e32 v78, v22, v22
	v_fmac_f32_e32 v78, v23, v23
	v_fmac_f32_e32 v78, v24, v24
	v_fmac_f32_e32 v78, v25, v25
	v_fmac_f32_e32 v78, v26, v26
	v_fmac_f32_e32 v78, v27, v27
	v_fmac_f32_e32 v78, v28, v28
	v_fmac_f32_e32 v78, v29, v29
	v_fmac_f32_e32 v78, v30, v30
	v_fmac_f32_e32 v78, v31, v31
	v_fmac_f32_e32 v78, v0, v0
	v_fmac_f32_e32 v78, v1, v1
	v_fmac_f32_e32 v78, v2, v2
	v_fmac_f32_e32 v78, v3, v3
	v_fmac_f32_e32 v78, v4, v4
	v_fmac_f32_e32 v78, v5, v5
	v_pk_mul_f32 v[76:77], v[6:7], v[6:7]
	v_pk_mul_f32 v[74:75], v[8:9], v[8:9]
	v_add_f32_e32 v76, v76, v78
	v_add_f32_e32 v76, v77, v76
	v_add_f32_e32 v74, v74, v76
	v_pk_mul_f32 v[72:73], v[10:11], v[10:11]
	v_add_f32_e32 v74, v75, v74
	v_add_f32_e32 v72, v72, v74
	v_pk_mul_f32 v[70:71], v[12:13], v[12:13]
	v_add_f32_e32 v72, v73, v72
	v_add_f32_e32 v70, v70, v72
	v_pk_mul_f32 v[68:69], v[14:15], v[14:15]
	v_add_f32_e32 v70, v71, v70
	v_add_f32_e32 v68, v68, v70
	v_add_f32_e32 v68, v69, v68
	ds_bpermute_b32 v69, v187, v68
	s_lshl_b32 s58, s63, 7
	s_ashr_i32 s63, s62, 31
	s_lshl_b64 s[62:63], s[62:63], 12
	s_add_u32 s62, s90, s62
	s_waitcnt lgkmcnt(0)
	v_add_f32_e32 v68, v68, v69
	v_fmamk_f32 v68, v68, 0x3c000000, v178
	v_mul_f32_e32 v69, 0x4b800000, v68
	v_cmp_gt_f32_e32 vcc, s75, v68
	s_addc_u32 s63, s91, s63
	s_lshl_b32 s58, s58, 1
	v_cndmask_b32_e32 v68, v68, v69, vcc
	v_rsq_f32_e32 v68, v68
	s_add_u32 s62, s62, s58
	v_mov_b32_e32 v155, v145
	s_addc_u32 s63, s63, 0
	v_mul_f32_e32 v69, 0x45800000, v68
	v_cndmask_b32_e32 v68, v68, v69, vcc
	v_mul_f32_e32 v48, v48, v68
	v_mul_f32_e32 v49, v49, v68
	s_waitcnt vmcnt(0)
; __device__ __forceinline__ unsigned cvt_pk_bf16(float lo, float hi) { unsigned r; asm volatile("v_cvt_pk_bf16_f32 %0, %1, %2" : "=v"(r) : "v"(lo), "v"(hi)); return r; }
; #define ATT_LAS __attribute__((address_space(3)))
; __device__ __forceinline__ void sb_task(ATT_LAS unsigned char* wl  , int b, int h, int qb, const bf16_t* __restrict__ SQ, const bf16_t* __restrict__ SK, const bf16_t* __restrict__ VT, const float* __restrict__ gout, bf16_t* __restrict__ MIXED) {
;     ...
; #pragma unroll
;     for (int e = 0; e < 4; ++e)
; #pragma unroll
;         for (int g4 = 0; g4 < 4; ++g4) { const int e0 = 32 * e + 8 * g4 + 4 * hh; const f32x4 g = *(const f32x4*)(gout + e0);
;             u32x2 w; w.x = cvt_pk_bf16(O[e][4 * g4] * rstd * g[0], O[e][4 * g4 + 1] * rstd * g[1]); w.y = cvt_pk_bf16(O[e][4 * g4 + 2] * rstd * g[2], O[e][4 * g4 + 3] * rstd * g[3]);
;             *(ATT_LAS u32x2*)(wl + r * OSTG_PITCH + e0 * 2) = w; }
;     asm volatile("s_waitcnt lgkmcnt(0)" ::: "memory");
;     bf16_t* obase = MIXED + (size_t)(b * 4096 + t0) * 2048 + 1024 + h * 128;
; #pragma unroll
;     for (int i = 0; i < 8; ++i) { const int c = lane + 64 * i, row = c >> 4, c16 = c & 15;
;         *(u32x4*)(obase + (size_t)row * 2048 + c16 * 8) = *(const ATT_LAS u32x4*)(wl + row * OSTG_PITCH + c16 * 16); }
;     asm volatile("s_waitcnt lgkmcnt(0)" ::: "memory");
; __global__ void __launch_bounds__(NWAVES * 64, 2) fwd(Params P) {
;     ...
;         for (int t = vcu * NWAVES + wave; t < 4096; t += G * NWAVES) att::sb_task(L + wave * 16384, t >> 10, (t >> 7) & 7, t & 127, SQ, SK, VT, sb_out_g, MIX);
	v_mul_f32_e32 v48, v80, v48
	v_mul_f32_e32 v49, v81, v49
	v_cvt_pk_bf16_f32 v64, v48, v49
	v_mul_f32_e32 v48, v50, v68
	v_mul_f32_e32 v49, v51, v68
	v_mul_f32_e32 v48, v82, v48
	v_mul_f32_e32 v49, v83, v49
	v_cvt_pk_bf16_f32 v65, v48, v49
	v_mul_f32_e32 v52, v52, v68
	v_mul_f32_e32 v53, v53, v68
	v_mul_f32_e32 v54, v54, v68
	v_mul_f32_e32 v55, v55, v68
	ds_write_b64 v179, v[64:65]
	v_mul_f32_e32 v32, v32, v68
	v_mul_f32_e32 v33, v33, v68
	v_mul_f32_e32 v34, v34, v68
	v_mul_f32_e32 v35, v35, v68
	v_mul_f32_e32 v36, v36, v68
	v_mul_f32_e32 v37, v37, v68
	v_mul_f32_e32 v38, v38, v68
	v_mul_f32_e32 v39, v39, v68
	v_mul_f32_e32 v16, v16, v68
	v_mul_f32_e32 v17, v17, v68
	v_mul_f32_e32 v18, v18, v68
	v_mul_f32_e32 v19, v19, v68
	v_mul_f32_e32 v20, v20, v68
	v_mul_f32_e32 v21, v21, v68
	v_mul_f32_e32 v22, v22, v68
	v_mul_f32_e32 v23, v23, v68
	v_mul_f32_e32 v0, v0, v68
	v_mul_f32_e32 v1, v1, v68
	v_mul_f32_e32 v2, v2, v68
	v_mul_f32_e32 v3, v3, v68
	v_mul_f32_e32 v4, v4, v68
	v_mul_f32_e32 v5, v5, v68
	v_mul_f32_e32 v6, v6, v68
	v_mul_f32_e32 v7, v7, v68
	v_mov_b32_e32 v157, v145
	v_mov_b32_e32 v159, v145
	v_mov_b32_e32 v161, v145
	v_mov_b32_e32 v163, v145
	v_mov_b32_e32 v165, v145
	v_mov_b32_e32 v167, v145
	v_mov_b32_e32 v169, v145
	v_mov_b32_e32 v171, v145
	s_add_i32 s0, s0, s70
	s_add_i32 s71, s71, s70
	s_cmpk_lt_i32 s0, 0x1000
	v_mul_f32_e32 v48, v84, v52
	v_mul_f32_e32 v49, v85, v53
	v_mul_f32_e32 v50, v86, v54
	v_mul_f32_e32 v51, v87, v55
	v_cvt_pk_bf16_f32 v52, v48, v49
	v_cvt_pk_bf16_f32 v53, v50, v51
	v_mul_f32_e32 v55, v56, v68
	v_mul_f32_e32 v56, v57, v68
	v_mul_f32_e32 v57, v58, v68
	v_mul_f32_e32 v58, v59, v68
	v_add_u32_e32 v54, v177, v176
	ds_write_b64 v54, v[52:53]
	v_mul_f32_e32 v54, v60, v68
	v_mul_f32_e32 v48, v88, v55
	v_mul_f32_e32 v49, v89, v56
	v_mul_f32_e32 v50, v90, v57
	v_mul_f32_e32 v51, v91, v58
	v_cvt_pk_bf16_f32 v52, v48, v49
	v_cvt_pk_bf16_f32 v53, v50, v51
	v_mul_f32_e32 v55, v61, v68
	v_mul_f32_e32 v56, v62, v68
	v_mul_f32_e32 v57, v63, v68
	ds_write_b64 v180, v[52:53]
	v_mul_f32_e32 v48, v92, v54
	v_mul_f32_e32 v49, v93, v55
	v_mul_f32_e32 v50, v94, v56
	v_mul_f32_e32 v51, v95, v57
	v_cvt_pk_bf16_f32 v52, v48, v49
	v_cvt_pk_bf16_f32 v53, v50, v51
	ds_write_b64 v181, v[52:53]
	v_mul_f32_e32 v32, v96, v32
	v_mul_f32_e32 v33, v97, v33
	v_mul_f32_e32 v34, v98, v34
	v_mul_f32_e32 v35, v99, v35
	v_cvt_pk_bf16_f32 v48, v32, v33
	v_cvt_pk_bf16_f32 v49, v34, v35
	ds_write_b64 v182, v[48:49]
	v_mul_f32_e32 v32, v100, v36
	v_mul_f32_e32 v33, v101, v37
	v_mul_f32_e32 v34, v102, v38
	v_mul_f32_e32 v35, v103, v39
	v_cvt_pk_bf16_f32 v36, v32, v33
	v_cvt_pk_bf16_f32 v37, v34, v35
	v_mul_f32_e32 v38, v40, v68
	v_mul_f32_e32 v39, v41, v68
	v_mul_f32_e32 v40, v42, v68
	v_mul_f32_e32 v41, v43, v68
	ds_write_b64 v183, v[36:37]
	v_mul_f32_e32 v32, v104, v38
	v_mul_f32_e32 v33, v105, v39
	v_mul_f32_e32 v34, v106, v40
	v_mul_f32_e32 v35, v107, v41
	v_cvt_pk_bf16_f32 v36, v32, v33
	v_cvt_pk_bf16_f32 v37, v34, v35
	v_mul_f32_e32 v38, v44, v68
	v_mul_f32_e32 v39, v45, v68
	v_mul_f32_e32 v40, v46, v68
	v_mul_f32_e32 v41, v47, v68
	ds_write_b64 v184, v[36:37]
	v_mul_f32_e32 v32, v108, v38
	v_mul_f32_e32 v33, v109, v39
	v_mul_f32_e32 v34, v110, v40
	v_mul_f32_e32 v35, v111, v41
	v_cvt_pk_bf16_f32 v36, v32, v33
	v_cvt_pk_bf16_f32 v37, v34, v35
	ds_write_b64 v185, v[36:37]
	v_mul_f32_e32 v16, v112, v16
	v_mul_f32_e32 v17, v113, v17
	v_mul_f32_e32 v18, v114, v18
	v_mul_f32_e32 v19, v115, v19
	v_cvt_pk_bf16_f32 v32, v16, v17
	v_cvt_pk_bf16_f32 v33, v18, v19
	ds_write_b64 v189, v[32:33]
	v_mul_f32_e32 v16, v116, v20
	v_mul_f32_e32 v17, v117, v21
	v_mul_f32_e32 v18, v118, v22
	v_mul_f32_e32 v19, v119, v23
	v_cvt_pk_bf16_f32 v20, v16, v17
	v_cvt_pk_bf16_f32 v21, v18, v19
	v_mul_f32_e32 v22, v24, v68
	v_mul_f32_e32 v23, v25, v68
	v_mul_f32_e32 v24, v26, v68
	v_mul_f32_e32 v25, v27, v68
	ds_write_b64 v190, v[20:21]
	v_mul_f32_e32 v16, v120, v22
	v_mul_f32_e32 v17, v121, v23
	v_mul_f32_e32 v18, v122, v24
	v_mul_f32_e32 v19, v123, v25
	v_cvt_pk_bf16_f32 v20, v16, v17
	v_cvt_pk_bf16_f32 v21, v18, v19
	v_mul_f32_e32 v22, v28, v68
	v_mul_f32_e32 v23, v29, v68
	v_mul_f32_e32 v24, v30, v68
	v_mul_f32_e32 v25, v31, v68
	ds_write_b64 v191, v[20:21]
	v_mul_f32_e32 v16, v124, v22
	v_mul_f32_e32 v17, v125, v23
	v_mul_f32_e32 v18, v126, v24
	v_mul_f32_e32 v19, v127, v25
	v_cvt_pk_bf16_f32 v20, v16, v17
	v_cvt_pk_bf16_f32 v21, v18, v19
	ds_write_b64 v192, v[20:21]
	v_mul_f32_e32 v0, v128, v0
	v_mul_f32_e32 v1, v129, v1
	v_mul_f32_e32 v2, v130, v2
	v_mul_f32_e32 v3, v131, v3
	v_cvt_pk_bf16_f32 v16, v0, v1
	v_cvt_pk_bf16_f32 v17, v2, v3
	ds_write_b64 v193, v[16:17]
	v_mul_f32_e32 v0, v132, v4
	v_mul_f32_e32 v1, v133, v5
	v_mul_f32_e32 v2, v134, v6
	v_mul_f32_e32 v3, v135, v7
	v_cvt_pk_bf16_f32 v4, v0, v1
	v_cvt_pk_bf16_f32 v5, v2, v3
	v_mul_f32_e32 v6, v8, v68
	v_mul_f32_e32 v7, v9, v68
	v_mul_f32_e32 v8, v10, v68
	v_mul_f32_e32 v9, v11, v68
	ds_write_b64 v194, v[4:5]
	v_mul_f32_e32 v0, v136, v6
	v_mul_f32_e32 v1, v137, v7
	v_mul_f32_e32 v2, v138, v8
	v_mul_f32_e32 v3, v139, v9
	v_cvt_pk_bf16_f32 v4, v0, v1
	v_cvt_pk_bf16_f32 v5, v2, v3
	v_lshl_add_u64 v[6:7], s[62:63], 0, v[154:155]
	v_lshl_add_u64 v[32:33], v[6:7], 0, v[156:157]
	v_lshl_add_u64 v[34:35], v[6:7], 0, v[158:159]
	v_lshl_add_u64 v[36:37], v[6:7], 0, v[160:161]
	v_lshl_add_u64 v[38:39], v[6:7], 0, v[162:163]
	v_lshl_add_u64 v[40:41], v[6:7], 0, v[164:165]
	v_lshl_add_u64 v[42:43], v[6:7], 0, v[166:167]
	v_lshl_add_u64 v[44:45], v[6:7], 0, v[168:169]
	v_lshl_add_u64 v[46:47], v[6:7], 0, v[170:171]
	v_mul_f32_e32 v6, v12, v68
	v_mul_f32_e32 v7, v13, v68
	v_mul_f32_e32 v8, v14, v68
	v_mul_f32_e32 v9, v15, v68
	ds_write_b64 v195, v[4:5]
	v_mul_f32_e32 v0, v140, v6
	v_mul_f32_e32 v1, v141, v7
	v_mul_f32_e32 v2, v142, v8
	v_mul_f32_e32 v3, v143, v9
	v_cvt_pk_bf16_f32 v0, v0, v1
	v_cvt_pk_bf16_f32 v1, v2, v3
	ds_write_b64 v196, v[0:1]
	s_waitcnt lgkmcnt(0)
	ds_read_b128 v[0:3], v197
	ds_read_b128 v[4:7], v197 offset:1088
	ds_read_b128 v[8:11], v197 offset:2176
	ds_read_b128 v[12:15], v197 offset:3264
	ds_read_b128 v[16:19], v197 offset:4352
	ds_read_b128 v[20:23], v197 offset:5440
	ds_read_b128 v[24:27], v197 offset:6528
	ds_read_b128 v[28:31], v197 offset:7616
	s_waitcnt lgkmcnt(7)
	global_store_dwordx4 v[32:33], v[0:3], off offset:2048
	s_waitcnt lgkmcnt(6)
	global_store_dwordx4 v[34:35], v[4:7], off offset:2048
	s_waitcnt lgkmcnt(5)
	global_store_dwordx4 v[36:37], v[8:11], off offset:2048
	s_waitcnt lgkmcnt(4)
	global_store_dwordx4 v[38:39], v[12:15], off offset:2048
	s_waitcnt lgkmcnt(3)
	global_store_dwordx4 v[40:41], v[16:19], off offset:2048
	s_waitcnt lgkmcnt(2)
	global_store_dwordx4 v[42:43], v[20:23], off offset:2048
	s_waitcnt lgkmcnt(1)
	global_store_dwordx4 v[44:45], v[24:27], off offset:2048
	s_waitcnt lgkmcnt(0)
	global_store_dwordx4 v[46:47], v[28:31], off offset:2048
	s_waitcnt lgkmcnt(0)
	s_cbranch_scc0 .LBB0_566
